# rotated tile loops: next tile's decode+loads now issued ahead of the transposition barrier (barrier moved to the head of the store half)
# speedup vs baseline: 1.0096x; 1.0056x over previous
; __device__ __forceinline__ void transpose_tile(const float* src, int ldsrc, int k0, int n0, bf16_t* dst, int ldd, const float* gain, int rowmode, float* T) {
;     const int tid = threadIdx.x;
;     { const int kk = tid >> 4, n4 = (tid & 15) * 4; const float* gp = gain ? gain : src;
;         const f32x4 v0 = *(const f32x4*)(src + (size_t)(k0 + kk) * ldsrc + n0 + n4), v1 = *(const f32x4*)(src + (size_t)(k0 + kk + 32) * ldsrc + n0 + n4);
;         float g0 = gp[k0 + kk], g1 = gp[k0 + kk + 32]; if (!gain) { g0 = 1.0f; g1 = 1.0f; }
; #pragma unroll
;         for (int j = 0; j < 4; ++j) { T[(n4 + j) * 65 + kk] = v0[j] * g0; T[(n4 + j) * 65 + kk + 32] = v1[j] * g1; } }
; __device__ __forceinline__ void weight_tile(const Params& P, int t, float* T) {
;     ...
;         const int kt = j / nnt, ntile = j % nnt; (void)nkt;
;         transpose_tile(src, ldsrc, kt * 64, ntile * 64, dst, ldd, gain, rowmode, T);
.LBB0_1220:
	s_and_b32 s41, 0xffff, s20
	v_cvt_f32_u32_e32 v0, s41
	s_and_b32 s41, s75, 0xffff
	v_cvt_f32_u32_e32 v1, s41
	v_rcp_iflag_f32_e32 v2, v0
	s_nop 0
	v_mul_f32_e32 v2, v1, v2
	v_trunc_f32_e32 v2, v2
	v_cvt_u32_f32_e32 v3, v2
	v_fma_f32 v1, -v2, v0, v1
	v_cmp_ge_f32_e64 s[44:45], |v1|, v0
	s_cmp_lg_u64 s[44:45], 0
	v_readfirstlane_b32 s41, v3
	s_addc_u32 s41, s41, 0
	s_and_b32 s44, s41, 0xffff
	s_mul_i32 s41, s41, s20
	s_sub_i32 s20, s75, s41
	s_lshl_b32 s41, s44, 6
	s_lshl_b32 s44, s20, 6
	s_cmp_eq_u64 s[42:43], 0
	v_or_b32_e32 v14, s41, v8
	s_cselect_b64 s[76:77], -1, 0
	s_and_b64 s[78:79], s[76:77], exec
	v_add_u32_e32 v2, 32, v14
	s_cselect_b32 s43, s39, s43
	s_cselect_b32 s42, s38, s42
	v_mul_hi_u32_u24_e32 v1, s40, v14
	v_mul_u32_u24_e32 v0, s40, v14
	s_lshl_b32 s20, s20, 8
	v_mul_hi_u32_u24_e32 v3, s40, v2
	v_mul_u32_u24_e32 v2, s40, v2
	v_lshl_add_u64 v[0:1], v[0:1], 2, s[38:39]
	s_and_b32 s20, s20, 0x3ff00
	v_lshl_add_u64 v[2:3], v[2:3], 2, s[38:39]
	v_lshl_add_u64 v[0:1], v[0:1], 0, s[20:21]
	v_lshl_add_u64 v[2:3], v[2:3], 0, s[20:21]
	v_lshlrev_b32_e32 v14, 2, v14
	v_lshl_add_u64 v[0:1], v[0:1], 0, v[4:5]
	global_load_dword v18, v14, s[42:43]
	global_load_dword v19, v14, s[42:43] offset:128
	v_lshl_add_u64 v[14:15], v[2:3], 0, v[4:5]
	global_load_dwordx4 v[0:3], v[0:1], off
	s_nop 0
	global_load_dwordx4 v[14:17], v[14:15], off
	s_bitcmp1_b32 s32, 0
	s_cbranch_scc1 .Lrot0_tail
	s_and_b32 s20, 0xffff, s44
	s_cmp_lt_i32 s74, 2
	s_mov_b64 s[38:39], -1
	s_waitcnt vmcnt(3)
	v_cndmask_b32_e64 v18, v18, 1.0, s[76:77]
	s_waitcnt vmcnt(2)
	v_cndmask_b32_e64 v19, v19, 1.0, s[76:77]
	s_waitcnt vmcnt(1)
	v_mul_f32_e32 v0, v0, v18
	s_waitcnt vmcnt(0)
	v_mul_f32_e32 v14, v14, v19
	v_mul_f32_e32 v1, v1, v18
	v_mul_f32_e32 v15, v15, v19
	v_mul_f32_e32 v2, v2, v18
	v_mul_f32_e32 v16, v16, v19
	v_mul_f32_e32 v3, v3, v18
	v_mul_f32_e32 v17, v17, v19
	ds_write2_b32 v11, v0, v14 offset1:32
	ds_write2_b32 v11, v1, v15 offset0:65 offset1:97
	ds_write2_b32 v11, v2, v16 offset0:130 offset1:162
	ds_write2_b32 v11, v3, v17 offset0:195 offset1:227
	s_branch .Lrot0_save
.Lrot0_mid:
	s_and_b32 s20, 0xffff, s44
	s_cmp_lt_i32 s74, 2
	s_mov_b64 s[38:39], -1
	s_waitcnt vmcnt(4)
	v_cndmask_b32_e64 v18, v18, 1.0, s[76:77]
	s_waitcnt vmcnt(3)
	v_cndmask_b32_e64 v19, v19, 1.0, s[76:77]
	s_waitcnt vmcnt(2)
	v_mul_f32_e32 v0, v0, v18
	s_waitcnt vmcnt(1)
	v_mul_f32_e32 v14, v14, v19
	v_mul_f32_e32 v1, v1, v18
	v_mul_f32_e32 v15, v15, v19
	v_mul_f32_e32 v2, v2, v18
	v_mul_f32_e32 v16, v16, v19
	v_mul_f32_e32 v3, v3, v18
	v_mul_f32_e32 v17, v17, v19
	ds_write2_b32 v11, v0, v14 offset1:32
	ds_write2_b32 v11, v1, v15 offset0:65 offset1:97
	ds_write2_b32 v11, v2, v16 offset0:130 offset1:162
	ds_write2_b32 v11, v3, v17 offset0:195 offset1:227
.Lrot0_save:
	v_mov_b32_e32 v200, s20
	v_mov_b32_e32 v201, s36
	v_mov_b32_e32 v202, s37
	v_mov_b32_e32 v204, s34
	v_mov_b32_e32 v205, s35
	s_lshl_b32 s100, s41, 1
	v_mov_b32_e32 v206, s100
	v_mov_b32_e32 v207, 0
	s_mov_b32 s97, s74
	s_bitset1_b32 s32, 0
	v_xor_b32_e32 v11, 0x8000, v11
	s_addk_i32 s3, 0xf0
	s_addk_i32 s63, 0xf0
	s_cmpk_gt_i32 s72, 0xb4f
	s_cbranch_scc1 .Lrot0_last
	s_branch .LBB0_1190

; __device__ __forceinline__ unsigned cvt_pk_bf16(float lo, float hi) { unsigned r; asm volatile("v_cvt_pk_bf16_f32 %0, %1, %2" : "=v"(r) : "v"(lo), "v"(hi)); return r; }
; __device__ __forceinline__ void transpose_tile(const float* src, int ldsrc, int k0, int n0, bf16_t* dst, int ldd, const float* gain, int rowmode, float* T) {
;     ...
;     __syncthreads();
;     { const int n = tid >> 3, k8 = (tid & 7) * 8; const float* tp = T + n * 65 + k8; u32x4 w;
;         w.x = cvt_pk_bf16(tp[0], tp[1]); w.y = cvt_pk_bf16(tp[2], tp[3]); w.z = cvt_pk_bf16(tp[4], tp[5]); w.w = cvt_pk_bf16(tp[6], tp[7]);
;         const int nn = n0 + n; int row;
;         if (rowmode == 1) row = (nn >> 7) * 256 + (nn & 127);
;         else if (rowmode == 2) row = (nn >> 7) * 256 + 128 + (nn & 127);
;         else if (rowmode == 3) row = nn < 1024 ? nn : (nn < 2048 ? nn + 1024 : nn - 1024);
;         else row = nn;
.Lrot0_tail:
	s_waitcnt lgkmcnt(0)
	s_barrier
	s_mov_b64 s[98:99], -1
	ds_read2_b32 v[136:137], v10 offset1:1
	ds_read2_b32 v[138:139], v10 offset0:2 offset1:3
	ds_read2_b32 v[156:157], v10 offset0:4 offset1:5
	ds_read2_b32 v[150:151], v10 offset0:6 offset1:7
	s_waitcnt lgkmcnt(0)
	v_cvt_pk_bf16_f32 v136, v136, v137
	v_cvt_pk_bf16_f32 v137, v138, v139
	v_cvt_pk_bf16_f32 v138, v156, v157
	v_cvt_pk_bf16_f32 v139, v150, v151
	v_add_u32_e32 v150, v200, v9
	s_cmp_lt_i32 s97, 2
	s_cbranch_scc1 .LBB0_1226
	s_cmp_gt_i32 s97, 2
	s_cbranch_scc0 .LBB0_1223
	v_cmp_gt_u32_e32 vcc, s64, v150
	s_mov_b64 s[98:99], 0
	s_nop 0
	v_cndmask_b32_e32 v151, v12, v13, vcc
	v_cmp_lt_u32_e32 vcc, s65, v150
	s_nop 1
	v_cndmask_b32_e32 v151, 0, v151, vcc
	v_add_u32_e32 v151, v151, v150

; __device__ __forceinline__ void transpose_tile(const float* src, int ldsrc, int k0, int n0, bf16_t* dst, int ldd, const float* gain, int rowmode, float* T) {
;     const int tid = threadIdx.x;
;     { const int kk = tid >> 4, n4 = (tid & 15) * 4; const float* gp = gain ? gain : src;
;         const f32x4 v0 = *(const f32x4*)(src + (size_t)(k0 + kk) * ldsrc + n0 + n4), v1 = *(const f32x4*)(src + (size_t)(k0 + kk + 32) * ldsrc + n0 + n4);
;         float g0 = gp[k0 + kk], g1 = gp[k0 + kk + 32]; if (!gain) { g0 = 1.0f; g1 = 1.0f; }
; #pragma unroll
;         for (int j = 0; j < 4; ++j) { T[(n4 + j) * 65 + kk] = v0[j] * g0; T[(n4 + j) * 65 + kk + 32] = v1[j] * g1; } }
; __device__ __forceinline__ void weight_tile(const Params& P, int t, float* T) {
;     ...
;         const int kt = j / nnt, ntile = j % nnt; (void)nkt;
;         transpose_tile(src, ldsrc, kt * 64, ntile * 64, dst, ldd, gain, rowmode, T);
.LBB0_2008:
	s_and_b32 s41, 0xffff, s30
	v_cvt_f32_u32_e32 v0, s41
	s_and_b32 s41, s82, 0xffff
	v_cvt_f32_u32_e32 v1, s41
	v_rcp_iflag_f32_e32 v2, v0
	s_nop 0
	v_mul_f32_e32 v2, v1, v2
	v_trunc_f32_e32 v2, v2
	v_cvt_u32_f32_e32 v3, v2
	v_fma_f32 v1, -v2, v0, v1
	v_cmp_ge_f32_e64 s[44:45], |v1|, v0
	s_cmp_lg_u64 s[44:45], 0
	v_readfirstlane_b32 s41, v3
	s_addc_u32 s41, s41, 0
	s_and_b32 s44, s41, 0xffff
	s_mul_i32 s41, s41, s30
	s_sub_i32 s30, s82, s41
	s_lshl_b32 s41, s44, 6
	s_lshl_b32 s44, s30, 6
	s_cmp_eq_u64 s[42:43], 0
	v_or_b32_e32 v14, s41, v8
	s_cselect_b64 s[66:67], -1, 0
	s_and_b64 s[82:83], s[66:67], exec
	v_add_u32_e32 v2, 32, v14
	s_cselect_b32 s43, s37, s43
	s_cselect_b32 s42, s36, s42
	v_mul_hi_u32_u24_e32 v1, s40, v14
	v_mul_u32_u24_e32 v0, s40, v14
	s_lshl_b32 s30, s30, 8
	v_mul_hi_u32_u24_e32 v3, s40, v2
	v_mul_u32_u24_e32 v2, s40, v2
	v_lshl_add_u64 v[0:1], v[0:1], 2, s[36:37]
	s_and_b32 s30, s30, 0x3ff00
	v_lshl_add_u64 v[2:3], v[2:3], 2, s[36:37]
	v_lshl_add_u64 v[0:1], v[0:1], 0, s[30:31]
	v_lshl_add_u64 v[2:3], v[2:3], 0, s[30:31]
	v_lshlrev_b32_e32 v14, 2, v14
	v_lshl_add_u64 v[0:1], v[0:1], 0, v[4:5]
	global_load_dword v18, v14, s[42:43]
	global_load_dword v19, v14, s[42:43] offset:128
	v_lshl_add_u64 v[14:15], v[2:3], 0, v[4:5]
	global_load_dwordx4 v[0:3], v[0:1], off
	s_nop 0
	global_load_dwordx4 v[14:17], v[14:15], off
	s_bitcmp1_b32 s32, 0
	s_cbranch_scc1 .Lrot6_tail
	s_and_b32 s30, 0xffff, s44
	s_cmp_lt_i32 s80, 2
	s_mov_b64 s[36:37], -1
	s_waitcnt vmcnt(3)
	v_cndmask_b32_e64 v18, v18, 1.0, s[66:67]
	s_waitcnt vmcnt(2)
	v_cndmask_b32_e64 v19, v19, 1.0, s[66:67]
	s_waitcnt vmcnt(1)
	v_mul_f32_e32 v0, v0, v18
	s_waitcnt vmcnt(0)
	v_mul_f32_e32 v14, v14, v19
	v_mul_f32_e32 v1, v1, v18
	v_mul_f32_e32 v15, v15, v19
	v_mul_f32_e32 v2, v2, v18
	v_mul_f32_e32 v16, v16, v19
	v_mul_f32_e32 v3, v3, v18
	v_mul_f32_e32 v17, v17, v19
	ds_write2_b32 v11, v0, v14 offset1:32
	ds_write2_b32 v11, v1, v15 offset0:65 offset1:97
	ds_write2_b32 v11, v2, v16 offset0:130 offset1:162
	ds_write2_b32 v11, v3, v17 offset0:195 offset1:227
	s_branch .Lrot6_save
.Lrot6_mid:
	s_and_b32 s30, 0xffff, s44
	s_cmp_lt_i32 s80, 2
	s_mov_b64 s[36:37], -1
	s_waitcnt vmcnt(4)
	v_cndmask_b32_e64 v18, v18, 1.0, s[66:67]
	s_waitcnt vmcnt(3)
	v_cndmask_b32_e64 v19, v19, 1.0, s[66:67]
	s_waitcnt vmcnt(2)
	v_mul_f32_e32 v0, v0, v18
	s_waitcnt vmcnt(1)
	v_mul_f32_e32 v14, v14, v19
	v_mul_f32_e32 v1, v1, v18
	v_mul_f32_e32 v15, v15, v19
	v_mul_f32_e32 v2, v2, v18
	v_mul_f32_e32 v16, v16, v19
	v_mul_f32_e32 v3, v3, v18
	v_mul_f32_e32 v17, v17, v19
	ds_write2_b32 v11, v0, v14 offset1:32
	ds_write2_b32 v11, v1, v15 offset0:65 offset1:97
	ds_write2_b32 v11, v2, v16 offset0:130 offset1:162
	ds_write2_b32 v11, v3, v17 offset0:195 offset1:227
.Lrot6_save:
	v_mov_b32_e32 v200, s30
	v_mov_b32_e32 v201, s38
	v_mov_b32_e32 v202, s39
	v_mov_b32_e32 v204, s34
	v_mov_b32_e32 v205, s35
	s_lshl_b32 s100, s41, 1
	v_mov_b32_e32 v206, s100
	v_mov_b32_e32 v207, 0
	s_mov_b32 s97, s80
	s_bitset1_b32 s32, 0
	v_xor_b32_e32 v11, 0x8000, v11
	s_add_i32 s30, s79, 0xffffff40
	s_cmpk_lt_i32 s79, 0x900
	s_cselect_b32 s30, s79, s30
	s_add_i32 s3, s30, 0x180
	s_cmpk_lt_i32 s79, 0x9c0
	s_cbranch_scc0 .Lrot6_last
	s_branch .LBB0_1983

; __device__ __forceinline__ unsigned cvt_pk_bf16(float lo, float hi) { unsigned r; asm volatile("v_cvt_pk_bf16_f32 %0, %1, %2" : "=v"(r) : "v"(lo), "v"(hi)); return r; }
; __device__ __forceinline__ void transpose_tile(const float* src, int ldsrc, int k0, int n0, bf16_t* dst, int ldd, const float* gain, int rowmode, float* T) {
;     ...
;     __syncthreads();
;     { const int n = tid >> 3, k8 = (tid & 7) * 8; const float* tp = T + n * 65 + k8; u32x4 w;
;         w.x = cvt_pk_bf16(tp[0], tp[1]); w.y = cvt_pk_bf16(tp[2], tp[3]); w.z = cvt_pk_bf16(tp[4], tp[5]); w.w = cvt_pk_bf16(tp[6], tp[7]);
;         const int nn = n0 + n; int row;
;         if (rowmode == 1) row = (nn >> 7) * 256 + (nn & 127);
;         else if (rowmode == 2) row = (nn >> 7) * 256 + 128 + (nn & 127);
;         else if (rowmode == 3) row = nn < 1024 ? nn : (nn < 2048 ? nn + 1024 : nn - 1024);
;         else row = nn;
.Lrot6_tail:
	s_waitcnt lgkmcnt(0)
	s_barrier
	s_mov_b64 s[98:99], -1
	ds_read2_b32 v[136:137], v10 offset1:1
	ds_read2_b32 v[138:139], v10 offset0:2 offset1:3
	ds_read2_b32 v[156:157], v10 offset0:4 offset1:5
	ds_read2_b32 v[150:151], v10 offset0:6 offset1:7
	s_waitcnt lgkmcnt(0)
	v_cvt_pk_bf16_f32 v136, v136, v137
	v_cvt_pk_bf16_f32 v137, v138, v139
	v_cvt_pk_bf16_f32 v138, v156, v157
	v_cvt_pk_bf16_f32 v139, v150, v151
	v_add_u32_e32 v150, v200, v9
	s_cmp_lt_i32 s97, 2
	s_cbranch_scc1 .LBB0_2014
	s_cmp_gt_i32 s97, 2
	s_cbranch_scc0 .LBB0_2011
	v_cmp_gt_u32_e32 vcc, s65, v150
	s_mov_b64 s[98:99], 0
	s_nop 0
	v_cndmask_b32_e32 v151, v12, v13, vcc
	v_cmp_lt_u32_e32 vcc, s76, v150
	s_nop 1
	v_cndmask_b32_e32 v151, 0, v151, vcc
	v_add_u32_e32 v151, v151, v150

; __device__ __forceinline__ void transpose_tile(const float* src, int ldsrc, int k0, int n0, bf16_t* dst, int ldd, const float* gain, int rowmode, float* T) {
;     ...
;     { const int kk = tid >> 4, n4 = (tid & 15) * 4; const float* gp = gain ? gain : src;
;         const f32x4 v0 = *(const f32x4*)(src + (size_t)(k0 + kk) * ldsrc + n0 + n4), v1 = *(const f32x4*)(src + (size_t)(k0 + kk + 32) * ldsrc + n0 + n4);
;         float g0 = gp[k0 + kk], g1 = gp[k0 + kk + 32]; if (!gain) { g0 = 1.0f; g1 = 1.0f; }
; #pragma unroll
;         for (int j = 0; j < 4; ++j) { T[(n4 + j) * 65 + kk] = v0[j] * g0; T[(n4 + j) * 65 + kk + 32] = v1[j] * g1; } }
;     __syncthreads();
;     { const int n = tid >> 3, k8 = (tid & 7) * 8; const float* tp = T + n * 65 + k8; u32x4 w;
;         w.x = cvt_pk_bf16(tp[0], tp[1]); w.y = cvt_pk_bf16(tp[2], tp[3]); w.z = cvt_pk_bf16(tp[4], tp[5]); w.w = cvt_pk_bf16(tp[6], tp[7]);
;         const int nn = n0 + n; int row;
;         if (rowmode == 1) row = (nn >> 7) * 256 + (nn & 127);
;         else if (rowmode == 2) row = (nn >> 7) * 256 + 128 + (nn & 127);
;         else if (rowmode == 3) row = nn < 1024 ? nn : (nn < 2048 ? nn + 1024 : nn - 1024);
;         else row = nn;
;         *(u32x4*)(dst + (size_t)row * ldd + k0 + k8) = w; }
;     __syncthreads();
; }
; __device__ __forceinline__ void weight_tile(const Params& P, int t, float* T) {
;     unsigned char* ws = P.ws;
;     {
;         int j = t; const float* src; int ldsrc, nkt, nnt; bf16_t* dst; int ldd; const float* gain = nullptr; int rowmode = 0;
;         if (j < 64) { const int gi = j >> 4; j &= 15; src = P.in[10] + (size_t)gi * 65536; ldsrc = 256; nkt = 4; nnt = 4; dst = (bf16_t*)(ws + O_WP) + (size_t)gi * 65536; ldd = 256; }
;         else if ((j -= 64) < 2816) { const int q = j / 704; j %= 704; const int layer = q >> 1, up = q & 1; src = P.in[up ? 19 : 18] + (size_t)layer * 1024 * 2816; ldsrc = 2816; nkt = 16; nnt = 44;
;             dst = (bf16_t*)(ws + O_WGU) + (size_t)layer * 5632 * 1024; ldd = 1024; gain = P.in[7] + layer * 1024; rowmode = 1 + up; }
;         else if ((j -= 2816) < 1408) { const int layer = j / 704; j %= 704; src = P.in[20] + (size_t)layer * 2816 * 1024; ldsrc = 1024; nkt = 44; nnt = 16; dst = (bf16_t*)(ws + O_WD) + (size_t)layer * 1024 * 2816; ldd = 2816; }
.LBB0_2211:
	s_and_b32 s39, 0xffff, s28
	v_cvt_f32_u32_e32 v0, s39
	s_and_b32 s39, s81, 0xffff
	v_cvt_f32_u32_e32 v1, s39
	v_rcp_iflag_f32_e32 v2, v0
	s_nop 0
	v_mul_f32_e32 v2, v1, v2
	v_trunc_f32_e32 v2, v2
	v_cvt_u32_f32_e32 v3, v2
	v_fma_f32 v1, -v2, v0, v1
	v_cmp_ge_f32_e64 s[42:43], |v1|, v0
	s_cmp_lg_u64 s[42:43], 0
	v_readfirstlane_b32 s39, v3
	s_addc_u32 s39, s39, 0
	s_and_b32 s42, s39, 0xffff
	s_mul_i32 s39, s39, s28
	s_sub_i32 s28, s81, s39
	s_lshl_b32 s39, s42, 6
	s_lshl_b32 s42, s28, 6
	s_cmp_eq_u64 s[40:41], 0
	v_or_b32_e32 v13, s39, v102
	s_cselect_b64 s[66:67], -1, 0
	s_and_b64 s[80:81], s[66:67], exec
	v_add_u32_e32 v2, 32, v13
	s_cselect_b32 s41, s35, s41
	s_cselect_b32 s40, s34, s40
	v_mul_hi_u32_u24_e32 v1, s38, v13
	v_mul_u32_u24_e32 v0, s38, v13
	s_lshl_b32 s28, s28, 8
	v_mul_hi_u32_u24_e32 v3, s38, v2
	v_mul_u32_u24_e32 v2, s38, v2
	v_lshl_add_u64 v[0:1], v[0:1], 2, s[34:35]
	s_and_b32 s28, s28, 0x3ff00
	v_lshl_add_u64 v[2:3], v[2:3], 2, s[34:35]
	v_lshl_add_u64 v[0:1], v[0:1], 0, s[28:29]
	v_lshl_add_u64 v[2:3], v[2:3], 0, s[28:29]
	v_lshlrev_b32_e32 v13, 2, v13
	v_lshl_add_u64 v[0:1], v[0:1], 0, v[4:5]
	global_load_dword v18, v13, s[40:41]
	s_nop 0
	global_load_dword v13, v13, s[40:41] offset:128
	v_lshl_add_u64 v[14:15], v[2:3], 0, v[4:5]
	global_load_dwordx4 v[0:3], v[0:1], off
	s_nop 0
	global_load_dwordx4 v[14:17], v[14:15], off
	s_bitcmp1_b32 s32, 0
	s_cbranch_scc1 .Lrot8_tail
	s_and_b32 s28, 0xffff, s42
	s_cmp_lt_i32 s79, 2
	s_mov_b64 s[34:35], -1
	s_waitcnt vmcnt(3)
	v_cndmask_b32_e64 v18, v18, 1.0, s[66:67]
	s_waitcnt vmcnt(2)
	v_cndmask_b32_e64 v13, v13, 1.0, s[66:67]
	s_waitcnt vmcnt(1)
	v_mul_f32_e32 v0, v0, v18
	s_waitcnt vmcnt(0)
	v_mul_f32_e32 v14, v14, v13
	v_mul_f32_e32 v1, v1, v18
	v_mul_f32_e32 v15, v15, v13
	v_mul_f32_e32 v2, v2, v18
	v_mul_f32_e32 v16, v16, v13
	v_mul_f32_e32 v3, v3, v18
	v_mul_f32_e32 v13, v17, v13
	ds_write2_b32 v10, v0, v14 offset1:32
	ds_write2_b32 v10, v1, v15 offset0:65 offset1:97
	ds_write2_b32 v10, v2, v16 offset0:130 offset1:162
	ds_write2_b32 v10, v3, v13 offset0:195 offset1:227
	s_branch .Lrot8_save
.Lrot8_mid:
	s_and_b32 s28, 0xffff, s42
	s_cmp_lt_i32 s79, 2
	s_mov_b64 s[34:35], -1
	s_waitcnt vmcnt(4)
	v_cndmask_b32_e64 v18, v18, 1.0, s[66:67]
	s_waitcnt vmcnt(3)
	v_cndmask_b32_e64 v13, v13, 1.0, s[66:67]
	s_waitcnt vmcnt(2)
	v_mul_f32_e32 v0, v0, v18
	s_waitcnt vmcnt(1)
	v_mul_f32_e32 v14, v14, v13
	v_mul_f32_e32 v1, v1, v18
	v_mul_f32_e32 v15, v15, v13
	v_mul_f32_e32 v2, v2, v18
	v_mul_f32_e32 v16, v16, v13
	v_mul_f32_e32 v3, v3, v18
	v_mul_f32_e32 v13, v17, v13
	ds_write2_b32 v10, v0, v14 offset1:32
	ds_write2_b32 v10, v1, v15 offset0:65 offset1:97
	ds_write2_b32 v10, v2, v16 offset0:130 offset1:162
	ds_write2_b32 v10, v3, v13 offset0:195 offset1:227
.Lrot8_save:
	v_mov_b32_e32 v200, s28
	v_mov_b32_e32 v201, s36
	v_mov_b32_e32 v202, s37
	v_mov_b32_e32 v204, s30
	v_mov_b32_e32 v205, s31
	s_lshl_b32 s100, s39, 1
	v_mov_b32_e32 v206, s100
	v_mov_b32_e32 v207, 0
	s_mov_b32 s97, s79
	s_bitset1_b32 s32, 0
	v_xor_b32_e32 v10, 0x8000, v10
	s_add_i32 s28, s46, 0x180
	s_cmpk_lt_i32 s46, 0x840
	s_mov_b32 s46, s28
	s_cbranch_scc0 .Lrot8_last
	s_branch .LBB0_2186

; __device__ __forceinline__ unsigned cvt_pk_bf16(float lo, float hi) { unsigned r; asm volatile("v_cvt_pk_bf16_f32 %0, %1, %2" : "=v"(r) : "v"(lo), "v"(hi)); return r; }
; __device__ __forceinline__ void transpose_tile(const float* src, int ldsrc, int k0, int n0, bf16_t* dst, int ldd, const float* gain, int rowmode, float* T) {
;     ...
;     { const int n = tid >> 3, k8 = (tid & 7) * 8; const float* tp = T + n * 65 + k8; u32x4 w;
;         w.x = cvt_pk_bf16(tp[0], tp[1]); w.y = cvt_pk_bf16(tp[2], tp[3]); w.z = cvt_pk_bf16(tp[4], tp[5]); w.w = cvt_pk_bf16(tp[6], tp[7]);
;         const int nn = n0 + n; int row;
;         if (rowmode == 1) row = (nn >> 7) * 256 + (nn & 127);
;         else if (rowmode == 2) row = (nn >> 7) * 256 + 128 + (nn & 127);
;         else if (rowmode == 3) row = nn < 1024 ? nn : (nn < 2048 ? nn + 1024 : nn - 1024);
;         else row = nn;
;         *(u32x4*)(dst + (size_t)row * ldd + k0 + k8) = w; }
.Lrot8_tail:
	s_waitcnt lgkmcnt(0)
	s_barrier
	s_mov_b64 s[98:99], -1
	ds_read2_b32 v[136:137], v9 offset1:1
	ds_read2_b32 v[138:139], v9 offset0:2 offset1:3
	ds_read2_b32 v[156:157], v9 offset0:4 offset1:5
	ds_read2_b32 v[150:151], v9 offset0:6 offset1:7
	v_add_u32_e32 v149, v200, v8
	s_waitcnt lgkmcnt(0)
	v_cvt_pk_bf16_f32 v136, v136, v137
	v_cvt_pk_bf16_f32 v137, v138, v139
	v_cvt_pk_bf16_f32 v138, v156, v157
	v_cvt_pk_bf16_f32 v139, v150, v151
	s_cmp_lt_i32 s97, 2
	s_cbranch_scc1 .LBB0_2217
	s_cmp_gt_i32 s97, 2
	s_cbranch_scc0 .LBB0_2214
	v_cmp_gt_u32_e32 vcc, s76, v149
	s_mov_b64 s[98:99], 0
	s_nop 0
	v_cndmask_b32_e32 v150, v11, v12, vcc
	v_cmp_lt_u32_e32 vcc, s77, v149
	s_nop 1
	v_cndmask_b32_e32 v150, 0, v150, vcc
	v_add_u32_e32 v150, v150, v149
